# same as previous version without the G1 DPP reduction (A/B for that change)
# speedup vs baseline: 1.0793x; 1.0118x over previous
.LBB0_82:
	s_or_b64 exec, exec, s[0:1]
	v_readlane_b32 s22, v245, 7
	v_readlane_b32 s23, v245, 8
	s_cmpk_lt_i32 s24, 0x4000
	s_waitcnt lgkmcnt(0)
	s_barrier
	s_cbranch_scc0 .LBB0_95
	s_ashr_i32 s25, s24, 31
	s_lshl_b64 s[0:1], s[24:25], 12
	s_add_u32 s0, s76, s0
	v_lshlrev_b32_e32 v38, 4, v37
	s_addc_u32 s1, s77, s1
	global_load_dwordx4 v[0:3], v38, s[78:79] offset:3072
	global_load_dwordx4 v[4:7], v38, s[78:79] offset:2048
	global_load_dwordx4 v[8:11], v38, s[78:79] offset:1024
	global_load_dwordx4 v[12:15], v38, s[78:79]
	global_load_dwordx4 v[16:19], v38, s[0:1] nt
	global_load_dwordx4 v[20:23], v38, s[0:1] offset:1024 nt
	global_load_dwordx4 v[24:27], v38, s[0:1] offset:2048 nt
	global_load_dwordx4 v[28:31], v38, s[0:1] offset:3072 nt
	v_and_b32_e32 v40, 16, v33
	v_cmp_eq_u32_e64 s[4:5], 0, v40
	v_and_b32_e32 v40, 8, v33
	v_and_b32_e32 v35, 64, v36
	v_cmp_eq_u32_e64 s[6:7], 0, v40
	v_and_b32_e32 v40, 4, v33
	v_add_u32_e32 v35, 64, v35
	v_cmp_eq_u32_e64 s[8:9], 0, v40
	v_xor_b32_e32 v40, 32, v36
	v_cmp_lt_i32_e32 vcc, v40, v35
	s_ashr_i32 s21, s15, 31
	s_ashr_i32 s22, s3, 31
	v_cndmask_b32_e32 v40, v36, v40, vcc
	v_lshlrev_b32_e32 v62, 2, v40
	v_xor_b32_e32 v40, 16, v36
	v_cmp_lt_i32_e32 vcc, v40, v35
	s_add_u32 s20, s15, s3
	s_addc_u32 s21, s21, s22
	v_cndmask_b32_e32 v40, v36, v40, vcc
	v_lshlrev_b32_e32 v63, 2, v40
	v_xor_b32_e32 v40, 8, v36
	v_cmp_lt_i32_e32 vcc, v40, v35
	s_lshl_b64 s[22:23], s[20:21], 5
	s_add_u32 s22, s92, s22
	v_cndmask_b32_e32 v40, v36, v40, vcc
	v_lshlrev_b32_e32 v64, 2, v40
	v_xor_b32_e32 v40, 4, v36
	v_cmp_lt_i32_e32 vcc, v40, v35
	v_cmp_gt_u32_e64 s[12:13], 32, v37
	s_addc_u32 s23, s93, s23
	v_cndmask_b32_e32 v40, v36, v40, vcc
	s_ashr_i32 s29, s28, 31
	v_lshlrev_b32_e32 v65, 2, v40
	v_xor_b32_e32 v40, 2, v36
	v_cmp_eq_u32_e64 s[10:11], 0, v34
	v_cndmask_b32_e64 v34, 8, 0, s[12:13]
	v_lshrrev_b32_e32 v33, 2, v33
	s_lshl_b64 s[26:27], s[28:29], 5
	s_lshl_b64 s[20:21], s[20:21], 11
	v_mov_b32_e32 v39, 0
	v_cmp_lt_i32_e32 vcc, v40, v35
	v_and_or_b32 v33, v33, 7, v34
	s_add_u32 s20, s74, s20
	v_cndmask_b32_e32 v40, v36, v40, vcc
	v_lshlrev_b32_e32 v34, 2, v33
	v_mov_b32_e32 v33, v39
	s_addc_u32 s21, s75, s21
	v_lshlrev_b32_e32 v66, 2, v40
	v_xor_b32_e32 v40, 1, v36
	v_lshl_add_u64 v[54:55], s[20:21], 0, v[32:33]
	s_add_i32 s20, s24, s28
	v_cmp_lt_i32_e32 vcc, v40, v35
	s_ashr_i32 s21, s20, 31
	s_lshl_b64 s[30:31], s[28:29], 11
	v_cndmask_b32_e32 v35, v36, v40, vcc
	s_lshl_b64 s[20:21], s[20:21], 12
	v_lshlrev_b32_e32 v67, 2, v35
	v_mov_b32_e32 v35, v39
	s_add_u32 s20, s76, s20
	v_lshl_add_u64 v[48:49], s[86:87], 0, v[34:35]
	v_lshl_add_u64 v[50:51], s[84:85], 0, v[34:35]
	v_lshl_add_u64 v[34:35], s[22:23], 0, v[34:35]
	s_mov_b64 s[22:23], 0x100000
	s_addc_u32 s21, s77, s21
	v_add_u32_e32 v61, 0, v38
	v_cmp_lt_u32_e64 s[0:1], 31, v37
	v_lshl_add_u64 v[52:53], v[34:35], 0, s[22:23]
	v_lshl_add_u64 v[56:57], s[20:21], 0, v[38:39]
	s_lshl_b64 s[34:35], s[28:29], 12
	v_mov_b32_e32 v68, 0x358637bd
	s_mov_b32 s3, 0xbfb8aa3b
	s_mov_b32 s15, 0x42ce8ed0
	s_mov_b32 s20, 0xc2b17218
	s_mov_b32 s21, 0x7f800000
	s_mov_b32 s22, 0x41a00000
	s_mov_b32 s23, 0x3fb8aa3b
	s_mov_b32 s25, 0xc2ce8ed0
	s_mov_b32 s29, 0x42b17218
	s_mov_b32 s42, 0x3f2aaaab
	v_mov_b32_e32 v69, 0x3ecc95a3
	s_mov_b32 s43, 0x3f317218
	s_mov_b32 s44, 0x33800000
	v_mov_b32_e32 v70, 0x7f800000
	v_mov_b32_e32 v58, 0x3f317218
	s_andn2_b64 s[38:39], s[10:11], s[0:1]
	s_mov_b64 s[40:41], exec
	s_and_b64 exec, exec, s[38:39]
	global_load_dword v136, v[48:49], off
	global_load_dword v137, v[50:51], off
	s_mov_b64 exec, s[40:41]
	s_waitcnt vmcnt(0)
	s_branch .LBB0_86
.LBB0_84:
	s_or_b64 exec, exec, s[40:41]
	v_mov_b32_e32 v33, v137
	v_mul_f32_e32 v34, 0x3fb8aa3b, v33
	v_rndne_f32_e32 v35, v34
	v_fma_f32 v36, v33, s23, -v34
	v_sub_f32_e32 v34, v34, v35
	v_fmac_f32_e32 v36, 0x32a5705f, v33
	v_add_f32_e32 v34, v34, v36
	v_cvt_i32_f32_e32 v35, v35
	v_exp_f32_e32 v34, v34
	v_cmp_ngt_f32_e32 vcc, s25, v33
	v_ldexp_f32 v34, v34, v35
	s_nop 0
	v_cndmask_b32_e32 v34, 0, v34, vcc
	v_cmp_nlt_f32_e32 vcc, s29, v33
	s_nop 1
	v_cndmask_b32_e32 v33, v70, v34, vcc
	v_mul_f32_e64 v32, v32, -v33
	global_store_dword v[52:53], v32, off

.LBB0_86:
	s_add_i32 s24, s24, s28
	s_cmpk_gt_i32 s24, 0x3fff
	s_waitcnt vmcnt(6)
	v_mov_b64_e32 v[34:35], v[30:31]
	v_mov_b64_e32 v[38:39], v[26:27]
	v_mov_b64_e32 v[42:43], v[22:23]
	v_mov_b64_e32 v[46:47], v[18:19]
	s_cselect_b64 s[36:37], -1, 0
	v_mov_b64_e32 v[32:33], v[28:29]
	v_mov_b64_e32 v[36:37], v[24:25]
	v_mov_b64_e32 v[40:41], v[20:21]
	v_mov_b64_e32 v[44:45], v[16:17]
	s_and_b64 vcc, exec, s[36:37]
	s_cbranch_vccnz .LBB0_88
	global_load_dwordx4 v[16:19], v[56:57], off nt
	global_load_dwordx4 v[20:23], v[56:57], off offset:1024 nt
	global_load_dwordx4 v[24:27], v[56:57], off offset:2048 nt
	global_load_dwordx4 v[28:31], v[56:57], off offset:3072 nt

.LBB0_91:
	s_andn2_saveexec_b64 s[40:41], s[40:41]
	s_cbranch_execz .LBB0_85
	v_mov_b32_e32 v33, v136
	v_add_f32_e32 v32, v32, v33
	v_cmp_nlt_f32_e32 vcc, s22, v32
	s_and_saveexec_b64 s[40:41], vcc
	s_cbranch_execz .LBB0_84
	v_mul_f32_e32 v33, 0x3fb8aa3b, v32
	v_rndne_f32_e32 v34, v33
	v_sub_f32_e32 v35, v33, v34
	v_fma_f32 v33, v32, s23, -v33
	v_fmac_f32_e32 v33, 0x32a5705f, v32
	v_add_f32_e32 v33, v35, v33
	v_cvt_i32_f32_e32 v34, v34
	v_exp_f32_e32 v33, v33
	v_cmp_ngt_f32_e32 vcc, s25, v32
	v_ldexp_f32 v33, v33, v34
	s_nop 0
	v_cndmask_b32_e32 v33, 0, v33, vcc
	v_cmp_nlt_f32_e32 vcc, s29, v32
	s_nop 1
	v_cndmask_b32_e32 v46, v70, v33, vcc
	v_add_f32_e32 v34, 1.0, v46
	v_add_f32_e32 v32, -1.0, v34
	v_sub_f32_e32 v33, v32, v34
	v_add_f32_e32 v33, 1.0, v33
	v_sub_f32_e32 v32, v46, v32
	v_add_f32_e32 v35, v32, v33
	v_frexp_mant_f32_e32 v36, v34
	v_cvt_f64_f32_e32 v[32:33], v34
	v_frexp_exp_i32_f64_e32 v32, v[32:33]
	v_cmp_gt_f32_e32 vcc, s42, v36
	s_nop 1
	v_subbrev_co_u32_e32 v40, vcc, 0, v32, vcc
	v_sub_u32_e32 v32, 0, v40
	v_ldexp_f32 v33, v34, v32
	v_add_f32_e32 v34, -1.0, v33
	v_add_f32_e32 v36, 1.0, v33
	v_ldexp_f32 v32, v35, v32
	v_add_f32_e32 v35, 1.0, v34
	v_add_f32_e32 v37, -1.0, v36
	v_sub_f32_e32 v35, v33, v35
	v_sub_f32_e32 v33, v33, v37
	v_add_f32_e32 v35, v32, v35
	v_add_f32_e32 v32, v32, v33
	v_add_f32_e32 v41, v36, v32
	v_rcp_f32_e32 v43, v41
	v_sub_f32_e32 v33, v36, v41
	v_add_f32_e32 v42, v32, v33
	v_add_f32_e32 v33, v34, v35
	v_mul_f32_e32 v45, v33, v43
	v_sub_f32_e32 v32, v34, v33
	v_mul_f32_e32 v34, v41, v45
	v_fma_f32 v36, v45, v41, -v34
	v_fmac_f32_e32 v36, v45, v42
	v_add_f32_e32 v44, v35, v32
	v_add_f32_e32 v32, v34, v36
	v_sub_f32_e32 v35, v33, v32
	v_pk_add_f32 v[38:39], v[32:33], v[34:35] neg_lo:[0,1] neg_hi:[0,1]
	v_mov_b32_e32 v37, v32
	v_pk_add_f32 v[32:33], v[38:39], v[36:37] neg_lo:[0,1] neg_hi:[0,1]
	v_cmp_neq_f32_e32 vcc, s21, v46
	v_add_f32_e32 v33, v44, v33
	v_add_f32_e32 v32, v32, v33
	v_add_f32_e32 v33, v35, v32
	v_mul_f32_e32 v44, v43, v33
	v_mul_f32_e32 v34, v41, v44
	v_fma_f32 v36, v44, v41, -v34
	v_fmac_f32_e32 v36, v44, v42
	v_sub_f32_e32 v35, v35, v33
	v_add_f32_e32 v41, v32, v35
	v_add_f32_e32 v32, v34, v36
	v_sub_f32_e32 v35, v33, v32
	v_pk_add_f32 v[38:39], v[32:33], v[34:35] neg_lo:[0,1] neg_hi:[0,1]
	v_mov_b32_e32 v37, v32
	v_pk_add_f32 v[32:33], v[38:39], v[36:37] neg_lo:[0,1] neg_hi:[0,1]
	s_nop 0
	v_add_f32_e32 v33, v41, v33
	v_add_f32_e32 v32, v32, v33
	v_add_f32_e32 v33, v45, v44
	v_add_f32_e32 v32, v35, v32
	v_sub_f32_e32 v34, v33, v45
	v_mul_f32_e32 v32, v43, v32
	v_sub_f32_e32 v34, v44, v34
	v_add_f32_e32 v34, v34, v32
	v_add_f32_e32 v36, v33, v34
	v_mul_f32_e32 v37, v36, v36
	v_fmamk_f32 v32, v37, 0x3e9b6dac, v69
	v_fmaak_f32 v59, v37, v32, 0x3f2aaada
	v_cvt_f32_i32_e32 v32, v40
	v_sub_f32_e32 v33, v36, v33
	v_sub_f32_e32 v33, v34, v33
	v_ldexp_f32 v38, v33, 1
	v_mul_f32_e32 v33, v36, v37
	v_ldexp_f32 v35, v36, 1
	v_pk_mul_f32 v[36:37], v[32:33], v[58:59]
	s_nop 0
	v_fma_f32 v34, v32, s43, -v36
	v_fmac_f32_e32 v34, 0xb102e308, v32
	v_pk_add_f32 v[32:33], v[36:37], v[34:35]
	s_nop 0
	v_sub_f32_e32 v35, v33, v35
	v_sub_f32_e32 v35, v37, v35
	v_add_f32_e32 v39, v38, v35
	v_mov_b32_e32 v38, v36
	v_pk_add_f32 v[36:37], v[32:33], v[36:37] neg_lo:[0,1] neg_hi:[0,1]
	v_pk_add_f32 v[40:41], v[32:33], v[38:39]
	v_mov_b32_e32 v35, v32
	v_mov_b32_e32 v37, v41
	v_pk_add_f32 v[42:43], v[34:35], v[36:37] neg_lo:[0,1] neg_hi:[0,1]
	v_pk_add_f32 v[34:35], v[34:35], v[36:37]
	v_mov_b32_e32 v38, v39
	v_pk_add_f32 v[36:37], v[34:35], v[32:33] op_sel:[1,0] op_sel_hi:[0,1] neg_lo:[0,1] neg_hi:[0,1]
	v_pk_add_f32 v[44:45], v[40:41], v[36:37] op_sel_hi:[1,0] neg_lo:[0,1] neg_hi:[0,1]
	v_mov_b32_e32 v40, v41
	v_mov_b32_e32 v41, v35
	v_pk_mov_b32 v[36:37], v[32:33], v[36:37] op_sel:[1,0]
	v_mov_b32_e32 v39, v32
	v_pk_add_f32 v[36:37], v[40:41], v[36:37] neg_lo:[0,1] neg_hi:[0,1]
	v_mov_b32_e32 v44, v42
	v_pk_add_f32 v[32:33], v[38:39], v[36:37] neg_lo:[0,1] neg_hi:[0,1]
	v_mov_b32_e32 v43, v35
	v_pk_add_f32 v[36:37], v[44:45], v[32:33]
	s_nop 0
	v_pk_add_f32 v[38:39], v[36:37], v[36:37] op_sel:[0,1] op_sel_hi:[1,0]
	s_nop 0
	v_pk_add_f32 v[34:35], v[34:35], v[38:39] op_sel:[1,0] op_sel_hi:[0,1]
	v_mov_b32_e32 v37, v34
	v_pk_add_f32 v[40:41], v[36:37], v[42:43] neg_lo:[0,1] neg_hi:[0,1]
	v_mov_b32_e32 v33, v38
	v_sub_f32_e32 v35, v36, v40
	v_pk_add_f32 v[32:33], v[32:33], v[40:41] neg_lo:[0,1] neg_hi:[0,1]
	v_sub_f32_e32 v35, v42, v35
	v_add_f32_e32 v32, v32, v35
	v_add_f32_e32 v32, v32, v33
	v_add_f32_e32 v32, v34, v32
	v_cndmask_b32_e32 v32, v70, v32, vcc
	v_cmp_lt_f32_e64 vcc, |v46|, s44
	s_nop 1
	v_cndmask_b32_e32 v32, v32, v46, vcc
	s_branch .LBB0_84

.LBB0_562:
	s_addk_i32 s83, 0x80
	s_add_u32 s36, s36, 64
	s_addc_u32 s37, s37, 0
	s_add_i32 s19, s19, 2
	s_and_b64 vcc, exec, s[6:7]
	s_cbranch_vccnz .Lg2_w16b
	s_waitcnt vmcnt(0)
	s_branch .Lg2_wdb
.Lg2_w16b:
	s_waitcnt vmcnt(16)
.Lg2_wdb:
	s_add_u32 s46, s46, 0x40000
	s_addc_u32 s47, s47, 0
	s_mov_b64 s[42:43], 0x20000
	v_lshl_add_u64 v[44:45], v[44:45], 0, s[42:43]
	v_lshl_add_u64 v[46:47], v[46:47], 0, s[16:17]
	s_cmp_lt_u32 s19, 30
	v_lshl_add_u64 v[48:49], v[48:49], 0, s[16:17]
	s_waitcnt lgkmcnt(0)
	s_barrier
	s_cbranch_scc0 .LBB0_554
.LBB0_563:
	s_add_u32 s48, s92, s36
	s_addc_u32 s49, s93, s37
	global_load_dword v0, v60, s[48:49]
	s_andn2_b64 vcc, exec, s[6:7]
	s_cbranch_vccnz .Lg2_nouA
	v_mov_b32_e32 v188, v58
	s_add_u32 s48, s92, s46
	s_addc_u32 s49, s93, s47
	v_add_u32_e32 v194, s78, v188
	v_ashrrev_i32_e32 v195, 31, v194
	v_add_u32_e32 v196, 64, v194
	v_ashrrev_i32_e32 v197, 31, v196
	v_add_u32_e32 v198, 0x80, v194
	v_ashrrev_i32_e32 v199, 31, v198
	v_add_u32_e32 v200, 0xc0, v194
	v_ashrrev_i32_e32 v201, 31, v200
	v_lshl_add_u64 v[194:195], v[194:195], 3, s[48:49]
	v_add_co_u32_e32 v194, vcc, 0xdd20000, v194
	s_nop 1
	v_addc_co_u32_e32 v195, vcc, 0, v195, vcc
	v_lshl_add_u64 v[196:197], v[196:197], 3, s[48:49]
	v_add_co_u32_e32 v196, vcc, 0xdd20000, v196
	s_nop 1
	v_addc_co_u32_e32 v197, vcc, 0, v197, vcc
	v_lshl_add_u64 v[198:199], v[198:199], 3, s[48:49]
	v_add_co_u32_e32 v198, vcc, 0xdd20000, v198
	s_nop 1
	v_addc_co_u32_e32 v199, vcc, 0, v199, vcc
	v_lshl_add_u64 v[200:201], v[200:201], 3, s[48:49]
	v_add_co_u32_e32 v200, vcc, 0xdd20000, v200
	s_nop 1
	v_addc_co_u32_e32 v201, vcc, 0, v201, vcc
	global_load_dwordx2 v[180:181], v[194:195], off
	global_load_dwordx2 v[182:183], v[196:197], off
	global_load_dwordx2 v[184:185], v[198:199], off
	global_load_dwordx2 v[186:187], v[200:201], off
.Lg2_nouA:
	v_lshl_add_u64 v[62:63], s[92:93], 0, v[46:47]
	s_mov_b32 m0, s71
	v_lshl_add_u64 v[64:65], v[62:63], 0, s[8:9]
	global_load_lds_dwordx4 v[64:65], off
	v_lshl_add_u64 v[64:65], s[92:93], 0, v[48:49]
	v_lshl_add_u64 v[66:67], v[64:65], 0, s[8:9]
	s_mov_b32 m0, s22
	v_lshl_add_u64 v[2:3], s[92:93], 0, v[44:45]
	global_load_lds_dwordx4 v[66:67], off
	v_lshl_add_u64 v[66:67], v[62:63], 0, s[10:11]
	s_mov_b32 m0, s23
	v_lshl_add_u64 v[62:63], v[62:63], 0, s[12:13]
	global_load_lds_dwordx4 v[66:67], off
	v_lshl_add_u64 v[66:67], v[64:65], 0, s[10:11]
	s_mov_b32 m0, s33
	v_cmp_ne_u32_e64 s[42:43], 1, v59
	global_load_lds_dwordx4 v[66:67], off
	s_mov_b32 m0, s50
	s_andn2_b64 vcc, exec, s[6:7]
	global_load_lds_dwordx4 v[62:63], off
	v_lshl_add_u64 v[62:63], v[64:65], 0, s[12:13]
	s_mov_b32 m0, s51
	s_nop 0
	global_load_lds_dwordx4 v[62:63], off
	s_mov_b32 m0, s64
	s_nop 0
	global_load_lds_dwordx4 v[2:3], off
	s_cbranch_vccnz .LBB0_565
	v_mov_b32_e32 v61, v58
	v_cvt_pk_bf16_f32 v62, v32, v33
	v_lshl_add_u32 v170, v61, 4, 0
	ds_read_b128 v[78:81], v170
	ds_read_b128 v[82:85], v170 offset:4096
	ds_read_b128 v[86:89], v170 offset:16384
	ds_read_b128 v[90:93], v170 offset:20480
	ds_read_b128 v[94:97], v170 offset:8192
	ds_read_b128 v[98:101], v170 offset:12288
	ds_read_b128 v[102:105], v170 offset:24576
	ds_read_b128 v[106:109], v170 offset:28672
	v_cvt_pk_bf16_f32 v63, v34, v35
	v_cvt_pk_bf16_f32 v64, v28, v29
	v_cvt_pk_bf16_f32 v65, v30, v31
	v_cvt_pk_bf16_f32 v66, v24, v25
	v_cvt_pk_bf16_f32 v67, v26, v27
	v_cvt_pk_bf16_f32 v68, v20, v21
	v_cvt_pk_bf16_f32 v69, v22, v23
	v_cvt_pk_bf16_f32 v70, v16, v17
	v_cvt_pk_bf16_f32 v71, v18, v19
	v_cvt_pk_bf16_f32 v72, v12, v13
	v_cvt_pk_bf16_f32 v73, v14, v15
	v_cvt_pk_bf16_f32 v74, v8, v9
	v_cvt_pk_bf16_f32 v75, v10, v11
	v_cvt_pk_bf16_f32 v76, v4, v5
	v_cvt_pk_bf16_f32 v77, v6, v7
	v_and_b32_e32 v171, 15, v61
	ds_read_b128 v[110:113], v170 offset:1024
	ds_read_b128 v[114:117], v170 offset:5120
	ds_read_b128 v[118:121], v170 offset:17408
	ds_read_b128 v[122:125], v170 offset:21504
	ds_read_b128 v[126:129], v170 offset:9216
	ds_read_b128 v[130:133], v170 offset:13312
	ds_read_b128 v[134:137], v170 offset:25600
	ds_read_b128 v[138:141], v170 offset:29696
	s_waitcnt lgkmcnt(0)
	v_mfma_f32_16x16x32_bf16 v[78:81], v[78:81], v[62:65], 0
	v_mfma_f32_16x16x32_bf16 v[86:89], v[86:89], v[62:65], 0
	v_mfma_f32_16x16x32_bf16 v[82:85], v[82:85], v[62:65], 0
	v_mfma_f32_16x16x32_bf16 v[90:93], v[90:93], v[62:65], 0
	v_mfma_f32_16x16x32_bf16 v[94:97], v[94:97], v[62:65], 0
	v_mfma_f32_16x16x32_bf16 v[102:105], v[102:105], v[62:65], 0
	v_mfma_f32_16x16x32_bf16 v[98:101], v[98:101], v[62:65], 0
	v_mfma_f32_16x16x32_bf16 v[62:65], v[106:109], v[62:65], 0
	ds_read_b128 v[106:109], v170 offset:2048
	ds_read_b128 v[142:145], v170 offset:6144
	ds_read_b128 v[146:149], v170 offset:18432
	ds_read_b128 v[150:153], v170 offset:22528
	ds_read_b128 v[154:157], v170 offset:10240
	ds_read_b128 v[158:161], v170 offset:14336
	ds_read_b128 v[162:165], v170 offset:26624
	ds_read_b128 v[166:169], v170 offset:30720
	v_mfma_f32_16x16x32_bf16 v[78:81], v[110:113], v[66:69], v[78:81]
	v_mfma_f32_16x16x32_bf16 v[86:89], v[118:121], v[66:69], v[86:89]
	v_mfma_f32_16x16x32_bf16 v[82:85], v[114:117], v[66:69], v[82:85]
	v_mfma_f32_16x16x32_bf16 v[90:93], v[122:125], v[66:69], v[90:93]
	v_mfma_f32_16x16x32_bf16 v[94:97], v[126:129], v[66:69], v[94:97]
	v_mfma_f32_16x16x32_bf16 v[102:105], v[134:137], v[66:69], v[102:105]
	v_mfma_f32_16x16x32_bf16 v[98:101], v[130:133], v[66:69], v[98:101]
	v_mfma_f32_16x16x32_bf16 v[62:65], v[138:141], v[66:69], v[62:65]
	ds_read_b128 v[66:69], v170 offset:3072
	ds_read_b128 v[110:113], v170 offset:7168
	ds_read_b128 v[114:117], v170 offset:19456
	ds_read_b128 v[118:121], v170 offset:23552
	ds_read_b128 v[122:125], v170 offset:11264
	ds_read_b128 v[126:129], v170 offset:15360
	ds_read_b128 v[130:133], v170 offset:27648
	ds_read_b128 v[134:137], v170 offset:31744
	s_waitcnt lgkmcnt(0)
	v_mfma_f32_16x16x32_bf16 v[78:81], v[106:109], v[70:73], v[78:81]
	v_mfma_f32_16x16x32_bf16 v[86:89], v[146:149], v[70:73], v[86:89]
	v_mfma_f32_16x16x32_bf16 v[82:85], v[142:145], v[70:73], v[82:85]
	v_mfma_f32_16x16x32_bf16 v[90:93], v[150:153], v[70:73], v[90:93]
	v_mfma_f32_16x16x32_bf16 v[94:97], v[154:157], v[70:73], v[94:97]
	v_mfma_f32_16x16x32_bf16 v[102:105], v[162:165], v[70:73], v[102:105]
	v_mfma_f32_16x16x32_bf16 v[98:101], v[158:161], v[70:73], v[98:101]
	v_mfma_f32_16x16x32_bf16 v[62:65], v[166:169], v[70:73], v[62:65]
	ds_read_b128 v[70:73], v170 offset:32768
	ds_read_b128 v[106:109], v170 offset:34816
	ds_read_b128 v[138:141], v170 offset:36864
	ds_read_b128 v[142:145], v170 offset:38912
	ds_read_b128 v[146:149], v170 offset:40960
	ds_read_b128 v[150:153], v170 offset:43008
	ds_read_b128 v[154:157], v170 offset:45056
	ds_read_b128 v[158:161], v170 offset:47104
	v_mfma_f32_16x16x32_bf16 v[66:69], v[66:69], v[74:77], v[78:81]
	v_mfma_f32_16x16x32_bf16 v[78:81], v[114:117], v[74:77], v[86:89]
	v_mfma_f32_16x16x32_bf16 v[82:85], v[110:113], v[74:77], v[82:85]
	v_mfma_f32_16x16x32_bf16 v[86:89], v[118:121], v[74:77], v[90:93]
	v_mfma_f32_16x16x32_bf16 v[90:93], v[122:125], v[74:77], v[94:97]
	v_mfma_f32_16x16x32_bf16 v[94:97], v[130:133], v[74:77], v[102:105]
	v_mfma_f32_16x16x32_bf16 v[98:101], v[126:129], v[74:77], v[98:101]
	v_mfma_f32_16x16x32_bf16 v[62:65], v[134:137], v[74:77], v[62:65]
	v_lshlrev_b32_e32 v2, 16, v50
	v_and_b32_e32 v3, 0xffff0000, v50
	v_lshlrev_b32_e32 v74, 16, v51
	v_and_b32_e32 v75, 0xffff0000, v51
	v_sub_f32_e32 v3, v3, v67
	v_sub_f32_e32 v2, v2, v66
	v_lshlrev_b32_e32 v66, 16, v52
	v_and_b32_e32 v67, 0xffff0000, v52
	v_sub_f32_e32 v69, v75, v69
	v_sub_f32_e32 v68, v74, v68
	v_lshlrev_b32_e32 v74, 16, v53
	v_and_b32_e32 v75, 0xffff0000, v53
	v_sub_f32_e32 v76, v67, v83
	v_sub_f32_e32 v77, v66, v82
	v_lshlrev_b32_e32 v66, 16, v54
	v_and_b32_e32 v67, 0xffff0000, v54
	v_sub_f32_e32 v75, v75, v85
	v_sub_f32_e32 v74, v74, v84
	v_lshlrev_b32_e32 v82, 16, v55
	v_and_b32_e32 v83, 0xffff0000, v55
	v_sub_f32_e32 v84, v67, v91
	v_sub_f32_e32 v85, v66, v90
	v_lshlrev_b32_e32 v66, 16, v56
	v_and_b32_e32 v67, 0xffff0000, v56
	v_lshlrev_b32_e32 v90, 16, v57
	v_and_b32_e32 v91, 0xffff0000, v57
	v_sub_f32_e32 v83, v83, v93
	v_sub_f32_e32 v82, v82, v92
	v_sub_f32_e32 v91, v91, v101
	v_sub_f32_e32 v90, v90, v100
	v_sub_f32_e32 v92, v67, v99
	v_sub_f32_e32 v93, v66, v98
	s_waitcnt vmcnt(11)
	v_pk_mul_f32 v[34:35], v[34:35], v[0:1] op_sel_hi:[1,0]
	v_pk_mul_f32 v[32:33], v[32:33], v[0:1] op_sel_hi:[1,0]
	v_pk_mul_f32 v[30:31], v[30:31], v[0:1] op_sel_hi:[1,0]
	v_pk_mul_f32 v[28:29], v[28:29], v[0:1] op_sel_hi:[1,0]
	v_pk_mul_f32 v[26:27], v[26:27], v[0:1] op_sel_hi:[1,0]
	v_pk_mul_f32 v[24:25], v[24:25], v[0:1] op_sel_hi:[1,0]
	v_pk_mul_f32 v[22:23], v[22:23], v[0:1] op_sel_hi:[1,0]
	v_pk_mul_f32 v[20:21], v[20:21], v[0:1] op_sel_hi:[1,0]
	v_pk_mul_f32 v[18:19], v[18:19], v[0:1] op_sel_hi:[1,0]
	v_pk_mul_f32 v[16:17], v[16:17], v[0:1] op_sel_hi:[1,0]
	v_pk_mul_f32 v[14:15], v[14:15], v[0:1] op_sel_hi:[1,0]
	v_pk_mul_f32 v[12:13], v[12:13], v[0:1] op_sel_hi:[1,0]
	v_pk_mul_f32 v[10:11], v[10:11], v[0:1] op_sel_hi:[1,0]
	v_pk_mul_f32 v[8:9], v[8:9], v[0:1] op_sel_hi:[1,0]
	v_pk_mul_f32 v[6:7], v[6:7], v[0:1] op_sel_hi:[1,0]
	v_pk_mul_f32 v[4:5], v[4:5], v[0:1] op_sel_hi:[1,0]
	v_cvt_pk_bf16_f32 v66, v2, v3
	v_cvt_pk_bf16_f32 v67, v68, v69
	v_cvt_pk_bf16_f32 v68, v77, v76
	v_cvt_pk_bf16_f32 v69, v74, v75
	v_cvt_pk_bf16_f32 v74, v85, v84
	v_cvt_pk_bf16_f32 v75, v82, v83
	v_cvt_pk_bf16_f32 v76, v93, v92
	v_cvt_pk_bf16_f32 v77, v90, v91
	ds_read_b128 v[82:85], v170 offset:33792
	ds_read_b128 v[90:93], v170 offset:35840
	ds_read_b128 v[98:101], v170 offset:37888
	ds_read_b128 v[102:105], v170 offset:39936
	ds_read_b128 v[110:113], v170 offset:41984
	ds_read_b128 v[114:117], v170 offset:44032
	ds_read_b128 v[118:121], v170 offset:46080
	ds_read_b128 v[122:125], v170 offset:48128
	s_waitcnt lgkmcnt(14)
	v_mfma_f32_16x16x32_bf16 v[32:35], v[70:73], v[66:69], v[32:35]
	v_mfma_f32_16x16x32_bf16 v[28:31], v[106:109], v[66:69], v[28:31]
	s_waitcnt lgkmcnt(13)
	v_mfma_f32_16x16x32_bf16 v[24:27], v[138:141], v[66:69], v[24:27]
	s_waitcnt lgkmcnt(12)
	v_mfma_f32_16x16x32_bf16 v[20:23], v[142:145], v[66:69], v[20:23]
	s_waitcnt lgkmcnt(11)
	v_mfma_f32_16x16x32_bf16 v[16:19], v[146:149], v[66:69], v[16:19]
	s_waitcnt lgkmcnt(10)
	v_mfma_f32_16x16x32_bf16 v[12:15], v[150:153], v[66:69], v[12:15]
	s_waitcnt lgkmcnt(9)
	v_mfma_f32_16x16x32_bf16 v[8:11], v[154:157], v[66:69], v[8:11]
	s_waitcnt lgkmcnt(8)
	v_mfma_f32_16x16x32_bf16 v[2:5], v[158:161], v[66:69], v[4:7]
	ds_read_b128 v[70:73], v170 offset:49152
	ds_read_b128 v[106:109], v170 offset:50176
	ds_read_b128 v[126:129], v170 offset:51200
	ds_read_b128 v[130:133], v170 offset:52224
	ds_read_b128 v[134:137], v170 offset:53248
	ds_read_b128 v[138:141], v170 offset:54272
	ds_read_b128 v[142:145], v170 offset:55296
	ds_read_b128 v[146:149], v170 offset:56320
	s_waitcnt lgkmcnt(14)
	v_mfma_f32_16x16x32_bf16 v[32:35], v[82:85], v[74:77], v[32:35]
	v_mfma_f32_16x16x32_bf16 v[28:31], v[90:93], v[74:77], v[28:31]
	s_waitcnt lgkmcnt(13)
	v_mfma_f32_16x16x32_bf16 v[24:27], v[98:101], v[74:77], v[24:27]
	s_waitcnt lgkmcnt(12)
	v_mfma_f32_16x16x32_bf16 v[20:23], v[102:105], v[74:77], v[20:23]
	s_waitcnt lgkmcnt(11)
	v_mfma_f32_16x16x32_bf16 v[16:19], v[110:113], v[74:77], v[16:19]
	s_waitcnt lgkmcnt(10)
	v_mfma_f32_16x16x32_bf16 v[12:15], v[114:117], v[74:77], v[12:15]
	s_waitcnt lgkmcnt(9)
	v_mfma_f32_16x16x32_bf16 v[8:11], v[118:121], v[74:77], v[8:11]
	s_waitcnt lgkmcnt(8)
	v_mfma_f32_16x16x32_bf16 v[4:7], v[122:125], v[74:77], v[2:5]
	s_waitcnt lgkmcnt(7)
	v_mfma_f32_16x16x32_bf16 v[70:73], v[70:73], v[66:69], v[78:81]
	s_waitcnt lgkmcnt(5)
	v_mfma_f32_16x16x32_bf16 v[78:81], v[126:129], v[66:69], v[86:89]
	s_waitcnt lgkmcnt(3)
	v_mfma_f32_16x16x32_bf16 v[82:85], v[134:137], v[66:69], v[94:97]
	s_waitcnt lgkmcnt(1)
	v_mfma_f32_16x16x32_bf16 v[62:65], v[142:145], v[66:69], v[62:65]
	v_mfma_f32_16x16x32_bf16 v[66:69], v[106:109], v[74:77], v[70:73]
	v_mfma_f32_16x16x32_bf16 v[70:73], v[130:133], v[74:77], v[78:81]
	v_mfma_f32_16x16x32_bf16 v[78:81], v[138:141], v[74:77], v[82:85]
	s_waitcnt lgkmcnt(0)
	v_mfma_f32_16x16x32_bf16 v[62:65], v[146:149], v[74:77], v[62:65]
	v_ashrrev_i32_e32 v0, 2, v61
	v_and_b32_e32 v0, -4, v0
	v_add_u32_e32 v2, s83, v0
	v_lshlrev_b32_e32 v0, 1, v171
	v_ashrrev_i32_e32 v3, 31, v2
	v_lshl_add_u64 v[74:75], s[28:29], 0, v[0:1]
	v_cvt_pk_bf16_f32 v0, v66, v67
	v_lshlrev_b64 v[66:67], 11, v[2:3]
	v_lshl_add_u64 v[66:67], v[74:75], 0, v[66:67]
	global_store_short v[66:67], v0, off
	global_store_short_d16_hi v[66:67], v0, off offset:2048
	v_add_co_u32_e32 v66, vcc, s72, v66
	v_cvt_pk_bf16_f32 v61, v68, v69
	s_nop 0
	v_addc_co_u32_e32 v67, vcc, 0, v67, vcc
	global_store_short v[66:67], v61, off
	global_store_short_d16_hi v[66:67], v61, off offset:2048
	v_add_u32_e32 v66, 16, v2
	v_ashrrev_i32_e32 v67, 31, v66
	v_lshlrev_b64 v[66:67], 11, v[66:67]
	v_cvt_pk_bf16_f32 v0, v70, v71
	v_lshl_add_u64 v[66:67], v[74:75], 0, v[66:67]
	global_store_short v[66:67], v0, off
	global_store_short_d16_hi v[66:67], v0, off offset:2048
	v_add_co_u32_e32 v66, vcc, s72, v66
	v_cvt_pk_bf16_f32 v3, v72, v73
	s_nop 0
	v_addc_co_u32_e32 v67, vcc, 0, v67, vcc
	global_store_short v[66:67], v3, off
	global_store_short_d16_hi v[66:67], v3, off offset:2048
	v_add_u32_e32 v66, 32, v2
	v_ashrrev_i32_e32 v67, 31, v66
	v_lshlrev_b64 v[66:67], 11, v[66:67]
	v_cvt_pk_bf16_f32 v0, v78, v79
	v_lshl_add_u64 v[66:67], v[74:75], 0, v[66:67]
	global_store_short v[66:67], v0, off
	global_store_short_d16_hi v[66:67], v0, off offset:2048
	v_add_co_u32_e32 v66, vcc, s72, v66
	v_cvt_pk_bf16_f32 v3, v80, v81
	s_nop 0
	v_addc_co_u32_e32 v67, vcc, 0, v67, vcc
	v_add_u32_e32 v2, 48, v2
	global_store_short v[66:67], v3, off
	global_store_short_d16_hi v[66:67], v3, off offset:2048
	v_ashrrev_i32_e32 v3, 31, v2
	v_lshlrev_b64 v[2:3], 11, v[2:3]
	v_cvt_pk_bf16_f32 v0, v62, v63
	v_lshl_add_u64 v[2:3], v[74:75], 0, v[2:3]
	global_store_short v[2:3], v0, off
	global_store_short_d16_hi v[2:3], v0, off offset:2048
	v_add_co_u32_e32 v2, vcc, 0x1000, v2
	v_cvt_pk_bf16_f32 v61, v64, v65
	s_nop 0
	v_addc_co_u32_e32 v3, vcc, 0, v3, vcc
	global_store_short v[2:3], v61, off
	global_store_short_d16_hi v[2:3], v61, off offset:2048

.LBB0_567:
	s_add_i32 s86, s19, 3
	s_and_b64 vcc, exec, s[6:7]
	s_cbranch_vccnz .Lg2_w16a
	s_waitcnt vmcnt(0)
	s_branch .Lg2_wda

.Lg2_wda:
	s_cmp_lt_u32 s86, 31
	s_cselect_b64 s[48:49], -1, 0
	s_add_u32 s96, s92, s36
	s_addc_u32 s97, s93, s37
	s_cmp_gt_u32 s86, 30
	s_waitcnt lgkmcnt(0)
	s_barrier
	global_load_dword v0, v60, s[96:97] offset:32
	s_cbranch_scc1 .LBB0_570
	s_andn2_b64 vcc, exec, s[6:7]
	s_cbranch_vccnz .Lg2_nouB
	v_mov_b32_e32 v188, v58
	s_add_i32 s96, s18, s19
	s_add_i32 s96, s96, 4
	s_ashr_i32 s97, s96, 31
	s_lshl_b64 s[96:97], s[96:97], 17
	s_add_u32 s96, s79, s96
	s_addc_u32 s97, s82, s97
	v_add_u32_e32 v194, s78, v188
	v_ashrrev_i32_e32 v195, 31, v194
	v_add_u32_e32 v196, 64, v194
	v_ashrrev_i32_e32 v197, 31, v196
	v_add_u32_e32 v198, 0x80, v194
	v_ashrrev_i32_e32 v199, 31, v198
	v_add_u32_e32 v200, 0xc0, v194
	v_ashrrev_i32_e32 v201, 31, v200
	v_lshl_add_u64 v[194:195], v[194:195], 3, s[96:97]
	v_lshl_add_u64 v[196:197], v[196:197], 3, s[96:97]
	v_lshl_add_u64 v[198:199], v[198:199], 3, s[96:97]
	v_lshl_add_u64 v[200:201], v[200:201], 3, s[96:97]
	global_load_dwordx2 v[50:51], v[194:195], off
	global_load_dwordx2 v[52:53], v[196:197], off
	global_load_dwordx2 v[54:55], v[198:199], off
	global_load_dwordx2 v[56:57], v[200:201], off
.Lg2_nouB:
	s_add_i32 s86, s18, s19
	s_add_i32 s86, s86, 4
	s_ashr_i32 s87, s86, 31
	s_lshl_b64 s[86:87], s[86:87], 3
	s_or_b64 s[86:87], s[86:87], s[4:5]
	s_lshl_b64 s[96:97], s[86:87], 14
	s_add_u32 vcc_lo, s26, s96
	s_addc_u32 vcc_hi, s27, s97
	s_lshl_b64 s[86:87], s[86:87], 13
	v_lshl_add_u64 v[2:3], v[38:39], 0, s[86:87]
	s_add_u32 s86, s24, s96
	s_addc_u32 s87, s25, s97
	s_add_u32 s96, s80, s96
	s_addc_u32 s97, s81, s97
	s_mov_b32 m0, s21
	v_lshl_add_u64 v[62:63], s[96:97], 0, v[36:37]
	global_load_lds_dwordx4 v[62:63], off
	v_lshl_add_u64 v[62:63], s[96:97], 0, v[40:41]
	s_mov_b32 m0, s65
	s_nop 0
	global_load_lds_dwordx4 v[62:63], off
	v_lshl_add_u64 v[62:63], s[86:87], 0, v[36:37]
	s_mov_b32 m0, s66
	s_nop 0
	global_load_lds_dwordx4 v[62:63], off
	v_lshl_add_u64 v[62:63], s[86:87], 0, v[40:41]
	s_mov_b32 m0, s67
	s_nop 0
	global_load_lds_dwordx4 v[62:63], off
	v_lshl_add_u64 v[62:63], vcc, 0, v[36:37]
	s_mov_b32 m0, s68
	s_nop 0
	global_load_lds_dwordx4 v[62:63], off
	v_lshl_add_u64 v[62:63], vcc, 0, v[40:41]
	s_mov_b32 m0, s69
	s_nop 0
	global_load_lds_dwordx4 v[62:63], off
	s_mov_b32 m0, s70
	s_nop 0
	global_load_lds_dwordx4 v[2:3], off
	s_and_b64 vcc, exec, s[42:43]
	s_cbranch_vccz .LBB0_571

.LBB0_571:
	v_mov_b32_e32 v61, v58
	v_cvt_pk_bf16_f32 v62, v32, v33
	v_lshl_add_u32 v2, v61, 4, 0
	v_add_u32_e32 v170, 0xe000, v2
	ds_read_b128 v[78:81], v2 offset:57344
	ds_read_b128 v[82:85], v2 offset:61440
	ds_read_b128 v[86:89], v170 offset:16384
	ds_read_b128 v[90:93], v170 offset:20480
	ds_read_b128 v[94:97], v170 offset:8192
	ds_read_b128 v[98:101], v170 offset:12288
	ds_read_b128 v[102:105], v170 offset:24576
	ds_read_b128 v[106:109], v170 offset:28672
	v_cvt_pk_bf16_f32 v63, v34, v35
	v_cvt_pk_bf16_f32 v64, v28, v29
	v_cvt_pk_bf16_f32 v65, v30, v31
	v_cvt_pk_bf16_f32 v66, v24, v25
	v_cvt_pk_bf16_f32 v67, v26, v27
	v_cvt_pk_bf16_f32 v68, v20, v21
	v_cvt_pk_bf16_f32 v69, v22, v23
	v_cvt_pk_bf16_f32 v70, v16, v17
	v_cvt_pk_bf16_f32 v71, v18, v19
	v_cvt_pk_bf16_f32 v72, v12, v13
	v_cvt_pk_bf16_f32 v73, v14, v15
	v_cvt_pk_bf16_f32 v74, v8, v9
	v_cvt_pk_bf16_f32 v75, v10, v11
	v_cvt_pk_bf16_f32 v76, v4, v5
	v_cvt_pk_bf16_f32 v77, v6, v7
	v_and_b32_e32 v171, 15, v61
	ds_read_b128 v[110:113], v2 offset:58368
	ds_read_b128 v[114:117], v2 offset:62464
	ds_read_b128 v[118:121], v170 offset:17408
	ds_read_b128 v[122:125], v170 offset:21504
	ds_read_b128 v[126:129], v170 offset:9216
	ds_read_b128 v[130:133], v170 offset:13312
	ds_read_b128 v[134:137], v170 offset:25600
	ds_read_b128 v[138:141], v170 offset:29696
	s_waitcnt lgkmcnt(0)
	v_mfma_f32_16x16x32_bf16 v[78:81], v[78:81], v[62:65], 0
	v_mfma_f32_16x16x32_bf16 v[86:89], v[86:89], v[62:65], 0
	v_mfma_f32_16x16x32_bf16 v[82:85], v[82:85], v[62:65], 0
	v_mfma_f32_16x16x32_bf16 v[90:93], v[90:93], v[62:65], 0
	v_mfma_f32_16x16x32_bf16 v[94:97], v[94:97], v[62:65], 0
	v_mfma_f32_16x16x32_bf16 v[102:105], v[102:105], v[62:65], 0
	v_mfma_f32_16x16x32_bf16 v[98:101], v[98:101], v[62:65], 0
	v_mfma_f32_16x16x32_bf16 v[62:65], v[106:109], v[62:65], 0
	ds_read_b128 v[106:109], v2 offset:59392
	ds_read_b128 v[142:145], v2 offset:63488
	ds_read_b128 v[146:149], v170 offset:18432
	ds_read_b128 v[150:153], v170 offset:22528
	ds_read_b128 v[154:157], v170 offset:10240
	ds_read_b128 v[158:161], v170 offset:14336
	ds_read_b128 v[162:165], v170 offset:26624
	ds_read_b128 v[166:169], v170 offset:30720
	v_mfma_f32_16x16x32_bf16 v[78:81], v[110:113], v[66:69], v[78:81]
	v_mfma_f32_16x16x32_bf16 v[86:89], v[118:121], v[66:69], v[86:89]
	v_mfma_f32_16x16x32_bf16 v[82:85], v[114:117], v[66:69], v[82:85]
	v_mfma_f32_16x16x32_bf16 v[90:93], v[122:125], v[66:69], v[90:93]
	v_mfma_f32_16x16x32_bf16 v[94:97], v[126:129], v[66:69], v[94:97]
	v_mfma_f32_16x16x32_bf16 v[102:105], v[134:137], v[66:69], v[102:105]
	v_mfma_f32_16x16x32_bf16 v[98:101], v[130:133], v[66:69], v[98:101]
	v_mfma_f32_16x16x32_bf16 v[62:65], v[138:141], v[66:69], v[62:65]
	ds_read_b128 v[66:69], v2 offset:60416
	ds_read_b128 v[110:113], v2 offset:64512
	ds_read_b128 v[114:117], v170 offset:19456
	ds_read_b128 v[118:121], v170 offset:23552
	ds_read_b128 v[122:125], v170 offset:11264
	ds_read_b128 v[126:129], v170 offset:15360
	ds_read_b128 v[130:133], v170 offset:27648
	ds_read_b128 v[134:137], v170 offset:31744
	s_waitcnt lgkmcnt(0)
	v_mfma_f32_16x16x32_bf16 v[78:81], v[106:109], v[70:73], v[78:81]
	v_mfma_f32_16x16x32_bf16 v[86:89], v[146:149], v[70:73], v[86:89]
	v_mfma_f32_16x16x32_bf16 v[82:85], v[142:145], v[70:73], v[82:85]
	v_mfma_f32_16x16x32_bf16 v[90:93], v[150:153], v[70:73], v[90:93]
	v_mfma_f32_16x16x32_bf16 v[94:97], v[154:157], v[70:73], v[94:97]
	v_mfma_f32_16x16x32_bf16 v[102:105], v[162:165], v[70:73], v[102:105]
	v_mfma_f32_16x16x32_bf16 v[98:101], v[158:161], v[70:73], v[98:101]
	v_mfma_f32_16x16x32_bf16 v[62:65], v[166:169], v[70:73], v[62:65]
	ds_read_b128 v[70:73], v170 offset:32768
	ds_read_b128 v[106:109], v170 offset:34816
	ds_read_b128 v[138:141], v170 offset:36864
	ds_read_b128 v[142:145], v170 offset:38912
	ds_read_b128 v[146:149], v170 offset:40960
	ds_read_b128 v[150:153], v170 offset:43008
	ds_read_b128 v[154:157], v170 offset:45056
	ds_read_b128 v[158:161], v170 offset:47104
	v_mfma_f32_16x16x32_bf16 v[66:69], v[66:69], v[74:77], v[78:81]
	v_mfma_f32_16x16x32_bf16 v[78:81], v[114:117], v[74:77], v[86:89]
	v_mfma_f32_16x16x32_bf16 v[82:85], v[110:113], v[74:77], v[82:85]
	v_mfma_f32_16x16x32_bf16 v[86:89], v[118:121], v[74:77], v[90:93]
	v_mfma_f32_16x16x32_bf16 v[90:93], v[122:125], v[74:77], v[94:97]
	v_mfma_f32_16x16x32_bf16 v[94:97], v[130:133], v[74:77], v[102:105]
	v_mfma_f32_16x16x32_bf16 v[98:101], v[126:129], v[74:77], v[98:101]
	v_mfma_f32_16x16x32_bf16 v[62:65], v[134:137], v[74:77], v[62:65]
	v_lshlrev_b32_e32 v2, 16, v180
	v_and_b32_e32 v3, 0xffff0000, v180
	v_lshlrev_b32_e32 v74, 16, v181
	v_and_b32_e32 v75, 0xffff0000, v181
	v_sub_f32_e32 v3, v3, v67
	v_sub_f32_e32 v2, v2, v66
	v_lshlrev_b32_e32 v66, 16, v182
	v_and_b32_e32 v67, 0xffff0000, v182
	v_sub_f32_e32 v69, v75, v69
	v_sub_f32_e32 v68, v74, v68
	v_lshlrev_b32_e32 v74, 16, v183
	v_and_b32_e32 v75, 0xffff0000, v183
	v_sub_f32_e32 v76, v67, v83
	v_sub_f32_e32 v77, v66, v82
	v_lshlrev_b32_e32 v66, 16, v184
	v_and_b32_e32 v67, 0xffff0000, v184
	v_sub_f32_e32 v75, v75, v85
	v_sub_f32_e32 v74, v74, v84
	v_lshlrev_b32_e32 v82, 16, v185
	v_and_b32_e32 v83, 0xffff0000, v185
	v_sub_f32_e32 v84, v67, v91
	v_sub_f32_e32 v85, v66, v90
	v_lshlrev_b32_e32 v66, 16, v186
	v_and_b32_e32 v67, 0xffff0000, v186
	v_lshlrev_b32_e32 v90, 16, v187
	v_and_b32_e32 v91, 0xffff0000, v187
	v_sub_f32_e32 v83, v83, v93
	v_sub_f32_e32 v82, v82, v92
	v_sub_f32_e32 v91, v91, v101
	v_sub_f32_e32 v90, v90, v100
	v_sub_f32_e32 v92, v67, v99
	v_sub_f32_e32 v93, v66, v98
	s_cmp_lg_u64 s[48:49], 0
	s_cbranch_scc1 .Lg2_w11
	s_waitcnt vmcnt(0)
	s_branch .Lg2_wd
.Lg2_w11:
	s_waitcnt vmcnt(11)
.Lg2_wd:
	v_pk_mul_f32 v[34:35], v[34:35], v[0:1] op_sel_hi:[1,0]
	v_pk_mul_f32 v[32:33], v[32:33], v[0:1] op_sel_hi:[1,0]
	v_pk_mul_f32 v[30:31], v[30:31], v[0:1] op_sel_hi:[1,0]
	v_pk_mul_f32 v[28:29], v[28:29], v[0:1] op_sel_hi:[1,0]
	v_pk_mul_f32 v[26:27], v[26:27], v[0:1] op_sel_hi:[1,0]
	v_pk_mul_f32 v[24:25], v[24:25], v[0:1] op_sel_hi:[1,0]
	v_pk_mul_f32 v[22:23], v[22:23], v[0:1] op_sel_hi:[1,0]
	v_pk_mul_f32 v[20:21], v[20:21], v[0:1] op_sel_hi:[1,0]
	v_pk_mul_f32 v[18:19], v[18:19], v[0:1] op_sel_hi:[1,0]
	v_pk_mul_f32 v[16:17], v[16:17], v[0:1] op_sel_hi:[1,0]
	v_pk_mul_f32 v[14:15], v[14:15], v[0:1] op_sel_hi:[1,0]
	v_pk_mul_f32 v[12:13], v[12:13], v[0:1] op_sel_hi:[1,0]
	v_pk_mul_f32 v[10:11], v[10:11], v[0:1] op_sel_hi:[1,0]
	v_pk_mul_f32 v[8:9], v[8:9], v[0:1] op_sel_hi:[1,0]
	v_pk_mul_f32 v[6:7], v[6:7], v[0:1] op_sel_hi:[1,0]
	v_pk_mul_f32 v[4:5], v[4:5], v[0:1] op_sel_hi:[1,0]
	v_cvt_pk_bf16_f32 v66, v2, v3
	v_cvt_pk_bf16_f32 v67, v68, v69
	v_cvt_pk_bf16_f32 v68, v77, v76
	v_cvt_pk_bf16_f32 v69, v74, v75
	v_cvt_pk_bf16_f32 v74, v85, v84
	v_cvt_pk_bf16_f32 v75, v82, v83
	v_cvt_pk_bf16_f32 v76, v93, v92
	v_cvt_pk_bf16_f32 v77, v90, v91
	ds_read_b128 v[82:85], v170 offset:33792
	ds_read_b128 v[90:93], v170 offset:35840
	ds_read_b128 v[98:101], v170 offset:37888
	ds_read_b128 v[102:105], v170 offset:39936
	ds_read_b128 v[110:113], v170 offset:41984
	ds_read_b128 v[114:117], v170 offset:44032
	ds_read_b128 v[118:121], v170 offset:46080
	ds_read_b128 v[122:125], v170 offset:48128
	s_waitcnt lgkmcnt(14)
	v_mfma_f32_16x16x32_bf16 v[32:35], v[70:73], v[66:69], v[32:35]
	v_mfma_f32_16x16x32_bf16 v[28:31], v[106:109], v[66:69], v[28:31]
	s_waitcnt lgkmcnt(13)
	v_mfma_f32_16x16x32_bf16 v[24:27], v[138:141], v[66:69], v[24:27]
	s_waitcnt lgkmcnt(12)
	v_mfma_f32_16x16x32_bf16 v[20:23], v[142:145], v[66:69], v[20:23]
	s_waitcnt lgkmcnt(11)
	v_mfma_f32_16x16x32_bf16 v[16:19], v[146:149], v[66:69], v[16:19]
	s_waitcnt lgkmcnt(10)
	v_mfma_f32_16x16x32_bf16 v[12:15], v[150:153], v[66:69], v[12:15]
	s_waitcnt lgkmcnt(9)
	v_mfma_f32_16x16x32_bf16 v[8:11], v[154:157], v[66:69], v[8:11]
	s_waitcnt lgkmcnt(8)
	v_mfma_f32_16x16x32_bf16 v[2:5], v[158:161], v[66:69], v[4:7]
	ds_read_b128 v[70:73], v170 offset:49152
	ds_read_b128 v[106:109], v170 offset:50176
	ds_read_b128 v[126:129], v170 offset:51200
	ds_read_b128 v[130:133], v170 offset:52224
	ds_read_b128 v[134:137], v170 offset:53248
	ds_read_b128 v[138:141], v170 offset:54272
	ds_read_b128 v[142:145], v170 offset:55296
	ds_read_b128 v[146:149], v170 offset:56320
	s_waitcnt lgkmcnt(14)
	v_mfma_f32_16x16x32_bf16 v[32:35], v[82:85], v[74:77], v[32:35]
	v_mfma_f32_16x16x32_bf16 v[28:31], v[90:93], v[74:77], v[28:31]
	s_waitcnt lgkmcnt(13)
	v_mfma_f32_16x16x32_bf16 v[24:27], v[98:101], v[74:77], v[24:27]
	s_waitcnt lgkmcnt(12)
	v_mfma_f32_16x16x32_bf16 v[20:23], v[102:105], v[74:77], v[20:23]
	s_waitcnt lgkmcnt(11)
	v_mfma_f32_16x16x32_bf16 v[16:19], v[110:113], v[74:77], v[16:19]
	s_waitcnt lgkmcnt(10)
	v_mfma_f32_16x16x32_bf16 v[12:15], v[114:117], v[74:77], v[12:15]
	s_waitcnt lgkmcnt(9)
	v_mfma_f32_16x16x32_bf16 v[8:11], v[118:121], v[74:77], v[8:11]
	s_waitcnt lgkmcnt(8)
	v_mfma_f32_16x16x32_bf16 v[4:7], v[122:125], v[74:77], v[2:5]
	s_waitcnt lgkmcnt(7)
	v_mfma_f32_16x16x32_bf16 v[70:73], v[70:73], v[66:69], v[78:81]
	s_waitcnt lgkmcnt(5)
	v_mfma_f32_16x16x32_bf16 v[78:81], v[126:129], v[66:69], v[86:89]
	s_waitcnt lgkmcnt(3)
	v_mfma_f32_16x16x32_bf16 v[82:85], v[134:137], v[66:69], v[94:97]
	s_waitcnt lgkmcnt(1)
	v_mfma_f32_16x16x32_bf16 v[62:65], v[142:145], v[66:69], v[62:65]
	v_mfma_f32_16x16x32_bf16 v[66:69], v[106:109], v[74:77], v[70:73]
	v_mfma_f32_16x16x32_bf16 v[70:73], v[130:133], v[74:77], v[78:81]
	v_mfma_f32_16x16x32_bf16 v[78:81], v[138:141], v[74:77], v[82:85]
	s_waitcnt lgkmcnt(0)
	v_mfma_f32_16x16x32_bf16 v[62:65], v[146:149], v[74:77], v[62:65]
	v_ashrrev_i32_e32 v0, 2, v61
	v_and_b32_e32 v0, -4, v0
	v_add_u32_e32 v61, s83, v0
	v_add_u32_e32 v2, 64, v61
	v_lshlrev_b32_e32 v0, 1, v171
	v_ashrrev_i32_e32 v3, 31, v2
	v_lshl_add_u64 v[74:75], s[28:29], 0, v[0:1]
	v_lshlrev_b64 v[2:3], 11, v[2:3]
	v_cvt_pk_bf16_f32 v0, v66, v67
	v_lshl_add_u64 v[2:3], v[74:75], 0, v[2:3]
	global_store_short v[2:3], v0, off
	global_store_short_d16_hi v[2:3], v0, off offset:2048
	v_add_co_u32_e32 v2, vcc, s72, v2
	v_cvt_pk_bf16_f32 v66, v68, v69
	s_nop 0
	v_addc_co_u32_e32 v3, vcc, 0, v3, vcc
	global_store_short v[2:3], v66, off
	global_store_short_d16_hi v[2:3], v66, off offset:2048
	v_add_u32_e32 v2, 0x50, v61
	v_ashrrev_i32_e32 v3, 31, v2
	v_lshlrev_b64 v[2:3], 11, v[2:3]
	v_cvt_pk_bf16_f32 v0, v70, v71
	v_lshl_add_u64 v[2:3], v[74:75], 0, v[2:3]
	global_store_short v[2:3], v0, off
	global_store_short_d16_hi v[2:3], v0, off offset:2048
	v_add_co_u32_e32 v2, vcc, s72, v2
	v_cvt_pk_bf16_f32 v66, v72, v73
	s_nop 0
	v_addc_co_u32_e32 v3, vcc, 0, v3, vcc
	global_store_short v[2:3], v66, off
	global_store_short_d16_hi v[2:3], v66, off offset:2048
	v_add_u32_e32 v2, 0x60, v61
	v_ashrrev_i32_e32 v3, 31, v2
	v_lshlrev_b64 v[2:3], 11, v[2:3]
	v_cvt_pk_bf16_f32 v0, v78, v79
	v_lshl_add_u64 v[2:3], v[74:75], 0, v[2:3]
	global_store_short v[2:3], v0, off
	global_store_short_d16_hi v[2:3], v0, off offset:2048
	v_add_co_u32_e32 v2, vcc, s72, v2
	v_cvt_pk_bf16_f32 v66, v80, v81
	s_nop 0
	v_addc_co_u32_e32 v3, vcc, 0, v3, vcc
	global_store_short v[2:3], v66, off
	global_store_short_d16_hi v[2:3], v66, off offset:2048
	v_add_u32_e32 v2, 0x70, v61
	v_ashrrev_i32_e32 v3, 31, v2
	v_lshlrev_b64 v[2:3], 11, v[2:3]
	v_cvt_pk_bf16_f32 v0, v62, v63
	v_lshl_add_u64 v[2:3], v[74:75], 0, v[2:3]
	global_store_short v[2:3], v0, off
	global_store_short_d16_hi v[2:3], v0, off offset:2048
	v_add_co_u32_e32 v2, vcc, 0x1000, v2
	v_cvt_pk_bf16_f32 v62, v64, v65
	s_nop 0
	v_addc_co_u32_e32 v3, vcc, 0, v3, vcc
	global_store_short v[2:3], v62, off
	global_store_short_d16_hi v[2:3], v62, off offset:2048
	s_and_b64 s[42:43], s[6:7], s[48:49]
	s_andn2_b64 vcc, exec, s[42:43]
	s_cbranch_vccnz .LBB0_562
.LBB0_572:
	s_branch .LBB0_562
.LBB0_573:
	v_readlane_b32 s20, v245, 62
	v_readlane_b32 s22, v244, 0
	v_readlane_b32 s21, v245, 63
	v_readlane_b32 s23, v244, 1
